# attention QK-to-PV transition: wait for first transposed V reads moved behind permlane block and counted per MFMA
# baseline (speedup 1.0000x reference)
; __device__ __forceinline__ void finishSM(f32x16& p0, f32x16& p1, float alpha, float& l_reg, bf16x8& pa0, bf16x8& pa1, bf16x8& pa2, bf16x8& pa3) {
; #pragma unroll
;   for (int r = 0; r < 16; ++r) p1[r] = __builtin_amdgcn_exp2f(p1[r]);
;   float ps = 0;
; #pragma unroll
;   for (int r = 0; r < 16; ++r) ps += p0[r];
; #pragma unroll
;   for (int r = 0; r < 16; ++r) ps += p1[r];
;   { auto rr = __builtin_amdgcn_permlane32_swap(__float_as_uint(ps), __float_as_uint(ps), false, false);
;     ps = __uint_as_float(rr[0]) + __uint_as_float(rr[1]); }
;   l_reg = l_reg * alpha + ps;
; template <bool MLA>
; __device__ __forceinline__ void qkt(f32x16& p0, f32x16& p1, const char* Ks, const char* KRs, const bf16x8* qr, const char* qrl, const f32x16& negm, int r32, int hi) {
; #pragma unroll
;   for (int d0 = 0; d0 < 8; ++d0) { int cb = (d0 * 16 + hi * 8) * 2;
;     bf16x8 b0 = *reinterpret_cast<const bf16x8*>(Ks + KSWZ(r32, cb));
;     bf16x8 b1 = *reinterpret_cast<const bf16x8*>(Ks + KSWZ(32 + r32, cb));
;     if (d0 == 0) { p0 = __builtin_amdgcn_mfma_f32_32x32x16_bf16(b0, qr[0], negm, 0, 0, 0); p1 = __builtin_amdgcn_mfma_f32_32x32x16_bf16(b1, qr[0], negm, 0, 0, 0); }
;     else { p0 = __builtin_amdgcn_mfma_f32_32x32x16_bf16(b0, qr[d0], p0, 0, 0, 0); p1 = __builtin_amdgcn_mfma_f32_32x32x16_bf16(b1, qr[d0], p1, 0, 0, 0); } }
;   if constexpr (MLA) {
; #pragma unroll
;     for (int d0 = 0; d0 < 4; ++d0) { int ch = d0 * 2 + hi;
;       bf16x8 b0 = *reinterpret_cast<const bf16x8*>(KRs + KRSWZ(r32, ch));
;       bf16x8 b1 = *reinterpret_cast<const bf16x8*>(KRs + KRSWZ(32 + r32, ch));
;       const bf16x8 qq = *reinterpret_cast<const bf16x8*>(qrl + d0 * 1024);
;       p0 = __builtin_amdgcn_mfma_f32_32x32x16_bf16(b0, qq, p0, 0, 0, 0);
;       p1 = __builtin_amdgcn_mfma_f32_32x32x16_bf16(b1, qq, p1, 0, 0, 0); }
;   }
.LBB0_101:
	s_mov_b32 s10, s24
	s_mov_b32 s24, s35
	s_lshl_b32 s2, s25, 14
	s_add_i32 s27, s2, 0
	s_add_i32 s32, s27, s15
	s_lshl_b32 s30, s25, 13
	s_lshl_b32 s11, s10, 14
	s_add_i32 s3, s11, 0
	v_add_u32_e32 v0, s3, v210
	ds_read_b128 v[234:237], v0 offset:57344
	ds_read_b128 v[98:101], v0 offset:49152
	v_add_u32_e32 v0, s3, v209
	s_lshl_b32 s2, s10, 13
	s_add_i32 s2, s2, 0
	s_add_i32 s2, s2, 0x18000
	s_add_u32 vcc_lo, s28, s46
	s_addc_u32 vcc_hi, s29, s47
	s_add_i32 m0, s32, 0xc000
	v_lshl_add_u64 v[250:251], v[172:173], 0, vcc
	global_load_lds_dwordx4 v[250:251], off
	v_exp_f32_e32 v213, v82
	v_add_f32_e32 v212, 0, v227
	v_add_f32_e32 v212, v229, v212
	s_waitcnt lgkmcnt(0)
	v_mfma_f32_32x32x16_bf16 v[114:129], v[98:101], v[158:161], v[66:81]
	v_exp_f32_e32 v246, v83
	v_add_f32_e32 v212, v225, v212
	v_add_f32_e32 v212, v228, v212
	s_lshl_b32 s31, s35, 14
	v_mfma_f32_32x32x16_bf16 v[98:113], v[234:237], v[158:161], v[66:81]
	ds_read_b128 v[234:237], v0 offset:57344
	ds_read_b128 v[238:241], v0 offset:49152
	v_add_u32_e32 v0, s3, v208
	s_add_u32 vcc_lo, s28, 0x4380100
	s_addc_u32 vcc_hi, s29, 0
	s_mov_b32 m0, s32
	v_lshl_add_u64 v[250:251], v[170:171], 0, vcc
	global_load_lds_dwordx4 v[250:251], off
	v_exp_f32_e32 v247, v84
	v_add_f32_e32 v212, v224, v212
	v_add_f32_e32 v212, v226, v212
	s_waitcnt lgkmcnt(0)
	v_mfma_f32_32x32x16_bf16 v[114:129], v[238:241], v[154:157], v[114:129]
	v_exp_f32_e32 v249, v85
	v_add_f32_e32 v212, v222, v212
	v_add_f32_e32 v212, v223, v212
	v_mfma_f32_32x32x16_bf16 v[98:113], v[234:237], v[154:157], v[98:113]
	ds_read_b128 v[234:237], v0 offset:57344
	ds_read_b128 v[238:241], v0 offset:49152
	v_add_u32_e32 v0, s3, v207
	s_add_u32 vcc_lo, s28, s46
	s_addc_u32 vcc_hi, s29, s47
	s_add_i32 m0, s32, 0xc400
	v_lshl_add_u64 v[250:251], v[174:175], 0, vcc
	global_load_lds_dwordx4 v[250:251], off
	v_exp_f32_e32 v252, v86
	v_add_f32_e32 v212, v219, v212
	v_add_f32_e32 v212, v221, v212
	s_waitcnt lgkmcnt(0)
	v_mfma_f32_32x32x16_bf16 v[114:129], v[238:241], v[150:153], v[114:129]
	v_exp_f32_e32 v253, v87
	v_add_f32_e32 v212, v218, v212
	v_add_f32_e32 v212, v220, v212
	v_mfma_f32_32x32x16_bf16 v[98:113], v[234:237], v[150:153], v[98:113]
	ds_read_b128 v[234:237], v0 offset:57344
	ds_read_b128 v[238:241], v0 offset:49152
	v_add_u32_e32 v0, s3, v206
	s_add_u32 vcc_lo, s28, 0x4380180
	s_addc_u32 vcc_hi, s29, 0
	s_add_i32 m0, s32, 0x400
	v_lshl_add_u64 v[250:251], v[170:171], 0, vcc
	global_load_lds_dwordx4 v[250:251], off
	v_exp_f32_e32 v254, v88
	v_add_f32_e32 v212, v215, v212
	v_add_f32_e32 v212, v217, v212
	s_waitcnt lgkmcnt(0)
	v_mfma_f32_32x32x16_bf16 v[114:129], v[238:241], v[146:149], v[114:129]
	v_exp_f32_e32 v255, v89
	v_add_f32_e32 v212, v214, v212
	v_add_f32_e32 v212, v216, v212
	v_mfma_f32_32x32x16_bf16 v[98:113], v[234:237], v[146:149], v[98:113]
	ds_read_b128 v[234:237], v0 offset:57344
	ds_read_b128 v[238:241], v0 offset:49152
	v_add_u32_e32 v0, s3, v205
	s_add_u32 vcc_lo, s28, 0x2e340600
	s_addc_u32 vcc_hi, s29, 0
	s_add_i32 m0, s23, s30
	v_lshl_add_u64 v[250:251], v[168:169], 0, vcc
	global_load_lds_dwordx4 v[250:251], off
	v_cvt_pk_bf16_f32 v82, v227, v229
	v_exp_f32_e32 v90, v90
	v_cvt_pk_bf16_f32 v83, v225, v228
	s_waitcnt lgkmcnt(0)
	v_mfma_f32_32x32x16_bf16 v[114:129], v[238:241], v[142:145], v[114:129]
	v_exp_f32_e32 v91, v91
	v_cvt_pk_bf16_f32 v84, v224, v226
	v_exp_f32_e32 v92, v92
	v_mfma_f32_32x32x16_bf16 v[98:113], v[234:237], v[142:145], v[98:113]
	ds_read_b128 v[234:237], v0 offset:57344
	ds_read_b128 v[238:241], v0 offset:49152
	v_add_u32_e32 v0, s3, v204
	v_cvt_pk_bf16_f32 v85, v222, v223
	v_exp_f32_e32 v93, v93
	v_cvt_pk_bf16_f32 v86, v219, v221
	s_waitcnt lgkmcnt(0)
	v_mfma_f32_32x32x16_bf16 v[114:129], v[238:241], v[138:141], v[114:129]
	v_exp_f32_e32 v94, v94
	v_cvt_pk_bf16_f32 v87, v218, v220
	v_exp_f32_e32 v95, v95
	v_mfma_f32_32x32x16_bf16 v[98:113], v[234:237], v[138:141], v[98:113]
	ds_read_b128 v[234:237], v0 offset:57344
	ds_read_b128 v[238:241], v0 offset:49152
	v_add_u32_e32 v0, s3, v203
	v_cvt_pk_bf16_f32 v88, v215, v217
	v_exp_f32_e32 v96, v96
	v_cvt_pk_bf16_f32 v89, v214, v216
	s_waitcnt lgkmcnt(0)
	v_mfma_f32_32x32x16_bf16 v[114:129], v[238:241], v[134:137], v[114:129]
	v_exp_f32_e32 v97, v97
	v_add_f32_e32 v212, v213, v212
	v_add_f32_e32 v212, v246, v212
	v_mfma_f32_32x32x16_bf16 v[98:113], v[234:237], v[134:137], v[98:113]
	ds_read_b128 v[234:237], v0 offset:57344
	ds_read_b128 v[238:241], v0 offset:49152
	v_add_u32_e32 v0, s2, v200
	v_add_f32_e32 v212, v247, v212
	v_add_f32_e32 v212, v249, v212
	v_add_f32_e32 v212, v252, v212
	s_waitcnt lgkmcnt(0)
	v_mfma_f32_32x32x16_bf16 v[114:129], v[238:241], v[130:133], v[114:129]
	v_add_f32_e32 v212, v253, v212
	v_add_f32_e32 v212, v254, v212
	v_add_f32_e32 v212, v255, v212
	v_mfma_f32_32x32x16_bf16 v[98:113], v[234:237], v[130:133], v[98:113]
	ds_read_b128 v[234:237], v0
	ds_read_b128 v[238:241], v0 offset:4096
	ds_read_b128 v[242:245], v198
	v_add_u32_e32 v0, s2, v201
	v_add_f32_e32 v212, v90, v212
	v_add_f32_e32 v212, v91, v212
	s_waitcnt lgkmcnt(0)
	v_mfma_f32_32x32x16_bf16 v[114:129], v[234:237], v[242:245], v[114:129]
	v_add_f32_e32 v212, v92, v212
	v_add_f32_e32 v212, v93, v212
	v_mfma_f32_32x32x16_bf16 v[98:113], v[238:241], v[242:245], v[98:113]
	ds_read_b128 v[234:237], v0
	ds_read_b128 v[238:241], v0 offset:4096
	ds_read_b128 v[242:245], v198 offset:1024
	v_add_u32_e32 v0, s2, v199
	v_add_f32_e32 v212, v94, v212
	v_add_f32_e32 v212, v95, v212
	s_waitcnt lgkmcnt(0)
; #define SBAR() __builtin_amdgcn_sched_barrier(0)
; __device__ __forceinline__ void finishSM(f32x16& p0, f32x16& p1, float alpha, float& l_reg, bf16x8& pa0, bf16x8& pa1, bf16x8& pa2, bf16x8& pa3) {
; #pragma unroll
;   for (int r = 0; r < 16; ++r) p1[r] = __builtin_amdgcn_exp2f(p1[r]);
;   float ps = 0;
; #pragma unroll
;   for (int r = 0; r < 16; ++r) ps += p0[r];
; #pragma unroll
;   for (int r = 0; r < 16; ++r) ps += p1[r];
;   { auto rr = __builtin_amdgcn_permlane32_swap(__float_as_uint(ps), __float_as_uint(ps), false, false);
;     ps = __uint_as_float(rr[0]) + __uint_as_float(rr[1]); }
;   l_reg = l_reg * alpha + ps;
;     ...
;   PK4(p0, 0, pa0); PK4(p0, 8, pa1); PK4(p1, 0, pa2); PK4(p1, 8, pa3);
; template <int D0> __device__ __forceinline__ void pv_one(f32x16& od, int vb, bf16x8 pa0, bf16x8 pa1, bf16x8 pa2, bf16x8 pa3) {
;   const s16x4 l0 = tr_read<v_rd_off(D0, 0, 0)>(vb), h0 = tr_read<v_rd_off(D0, 0, 1)>(vb), l1 = tr_read<v_rd_off(D0, 1, 0)>(vb), h1 = tr_read<v_rd_off(D0, 1, 1)>(vb);
;   const s16x4 l2 = tr_read<v_rd_off(D0, 2, 0)>(vb), h2 = tr_read<v_rd_off(D0, 2, 1)>(vb), l3 = tr_read<v_rd_off(D0, 3, 0)>(vb), h3 = tr_read<v_rd_off(D0, 3, 1)>(vb);
;   asm volatile("s_waitcnt lgkmcnt(0)" ::: "memory"); SBAR();
;     ...
;   od = __builtin_amdgcn_mfma_f32_32x32x16_bf16(pa0, PK(l0, h0), od, 0, 0, 0);
;   od = __builtin_amdgcn_mfma_f32_32x32x16_bf16(pa1, PK(l1, h1), od, 0, 0, 0);
;   od = __builtin_amdgcn_mfma_f32_32x32x16_bf16(pa2, PK(l2, h2), od, 0, 0, 0);
;   od = __builtin_amdgcn_mfma_f32_32x32x16_bf16(pa3, PK(l3, h3), od, 0, 0, 0);
;     ...
; }
; __device__ __forceinline__ void pv_d0(f32x16* o, int vb, bf16x8 pa0, bf16x8 pa1, bf16x8 pa2, bf16x8 pa3) {
;   pv_one<0>(o[0], vb, pa0, pa1, pa2, pa3); pv_one<1>(o[1], vb, pa0, pa1, pa2, pa3); pv_one<2>(o[2], vb, pa0, pa1, pa2, pa3); pv_one<3>(o[3], vb, pa0, pa1, pa2, pa3);
	v_mfma_f32_32x32x16_bf16 v[114:129], v[234:237], v[242:245], v[114:129]
	v_add_f32_e32 v212, v96, v212
	v_add_f32_e32 v212, v97, v212
	v_mfma_f32_32x32x16_bf16 v[98:113], v[238:241], v[242:245], v[98:113]
	ds_read_b128 v[234:237], v0
	ds_read_b128 v[238:241], v0 offset:4096
	ds_read_b128 v[242:245], v198 offset:2048
	v_add_u32_e32 v0, s2, v202
	v_cvt_pk_bf16_f32 v97, v96, v97
	v_cvt_pk_bf16_f32 v96, v94, v95
	s_waitcnt lgkmcnt(0)
	v_mfma_f32_32x32x16_bf16 v[114:129], v[234:237], v[242:245], v[114:129]
	v_cvt_pk_bf16_f32 v95, v92, v93
	v_cvt_pk_bf16_f32 v94, v90, v91
	v_mfma_f32_32x32x16_bf16 v[98:113], v[238:241], v[242:245], v[98:113]
	ds_read_b128 v[234:237], v0
	ds_read_b128 v[238:241], v0 offset:4096
	ds_read_b128 v[242:245], v198 offset:3072
	v_cvt_pk_bf16_f32 v90, v213, v246
	v_cvt_pk_bf16_f32 v91, v247, v249
	s_waitcnt lgkmcnt(0)
	v_mfma_f32_32x32x16_bf16 v[114:129], v[234:237], v[242:245], v[114:129]
	v_cvt_pk_bf16_f32 v92, v252, v253
	v_cvt_pk_bf16_f32 v93, v254, v255
	v_mfma_f32_32x32x16_bf16 v[98:113], v[238:241], v[242:245], v[98:113]
	v_add_u32_e32 v213, s31, v197
	ds_read_b64_tr_b16 v[214:215], v213 offset:0
	ds_read_b64_tr_b16 v[216:217], v213 offset:0x800
	ds_read_b64_tr_b16 v[218:219], v213 offset:0x1000
	ds_read_b64_tr_b16 v[220:221], v213 offset:0x1800
	ds_read_b64_tr_b16 v[222:223], v213 offset:0x2000
	ds_read_b64_tr_b16 v[224:225], v213 offset:0x2800
	ds_read_b64_tr_b16 v[226:227], v213 offset:0x3000
	ds_read_b64_tr_b16 v[228:229], v213 offset:0x3800
	v_mov_b32_e32 v0, v212
	s_nop 1
	v_permlane32_swap_b32_e32 v0, v212
	v_permlane32_swap_b32_e32 v82, v84
	v_permlane32_swap_b32_e32 v83, v85
	v_permlane32_swap_b32_e32 v86, v88
	v_permlane32_swap_b32_e32 v87, v89
	v_permlane32_swap_b32_e32 v90, v92
	v_permlane32_swap_b32_e32 v91, v93
	v_permlane32_swap_b32_e32 v94, v96
	v_permlane32_swap_b32_e32 v95, v97
	s_waitcnt lgkmcnt(6)
	v_mfma_f32_32x32x16_bf16 v[50:65], v[82:85], v[214:217], v[50:65]
	ds_read_b64_tr_b16 v[214:215], v213 offset:0x200
	ds_read_b64_tr_b16 v[216:217], v213 offset:0xa00
	s_waitcnt lgkmcnt(6)
	v_mfma_f32_32x32x16_bf16 v[50:65], v[86:89], v[218:221], v[50:65]
	ds_read_b64_tr_b16 v[218:219], v213 offset:0x1200
	ds_read_b64_tr_b16 v[220:221], v213 offset:0x1a00
	s_waitcnt lgkmcnt(6)
	v_mfma_f32_32x32x16_bf16 v[50:65], v[90:93], v[222:225], v[50:65]
	ds_read_b64_tr_b16 v[222:223], v213 offset:0x2200
	ds_read_b64_tr_b16 v[224:225], v213 offset:0x2a00
	s_waitcnt lgkmcnt(6)
	v_mfma_f32_32x32x16_bf16 v[50:65], v[94:97], v[226:229], v[50:65]
	ds_read_b64_tr_b16 v[226:227], v213 offset:0x3200
	ds_read_b64_tr_b16 v[228:229], v213 offset:0x3a00
	s_waitcnt lgkmcnt(6)
	v_mfma_f32_32x32x16_bf16 v[34:49], v[82:85], v[214:217], v[34:49]
	ds_read_b64_tr_b16 v[214:215], v213 offset:0x400
	ds_read_b64_tr_b16 v[216:217], v213 offset:0xc00
	s_waitcnt lgkmcnt(6)
	v_mfma_f32_32x32x16_bf16 v[34:49], v[86:89], v[218:221], v[34:49]
	ds_read_b64_tr_b16 v[218:219], v213 offset:0x1400
	ds_read_b64_tr_b16 v[220:221], v213 offset:0x1c00
	s_waitcnt lgkmcnt(6)
	v_mfma_f32_32x32x16_bf16 v[34:49], v[90:93], v[222:225], v[34:49]
	ds_read_b64_tr_b16 v[222:223], v213 offset:0x2400
	ds_read_b64_tr_b16 v[224:225], v213 offset:0x2c00
	s_waitcnt lgkmcnt(6)
	v_mfma_f32_32x32x16_bf16 v[34:49], v[94:97], v[226:229], v[34:49]
	ds_read_b64_tr_b16 v[226:227], v213 offset:0x3400
	ds_read_b64_tr_b16 v[228:229], v213 offset:0x3c00
	s_waitcnt lgkmcnt(6)
	v_mfma_f32_32x32x16_bf16 v[18:33], v[82:85], v[214:217], v[18:33]
	ds_read_b64_tr_b16 v[214:215], v213 offset:0x600
	ds_read_b64_tr_b16 v[216:217], v213 offset:0xe00
	s_waitcnt lgkmcnt(6)
	v_mfma_f32_32x32x16_bf16 v[18:33], v[86:89], v[218:221], v[18:33]
	ds_read_b64_tr_b16 v[218:219], v213 offset:0x1600
	ds_read_b64_tr_b16 v[220:221], v213 offset:0x1e00
	s_waitcnt lgkmcnt(6)
	v_mfma_f32_32x32x16_bf16 v[18:33], v[90:93], v[222:225], v[18:33]
	ds_read_b64_tr_b16 v[222:223], v213 offset:0x2600
	ds_read_b64_tr_b16 v[224:225], v213 offset:0x2e00
	s_waitcnt lgkmcnt(6)
	v_mfma_f32_32x32x16_bf16 v[18:33], v[94:97], v[226:229], v[18:33]
	ds_read_b64_tr_b16 v[226:227], v213 offset:0x3600
	ds_read_b64_tr_b16 v[228:229], v213 offset:0x3e00
	s_waitcnt lgkmcnt(6)
	v_mfma_f32_32x32x16_bf16 v[2:17], v[82:85], v[214:217], v[2:17]
	v_max_f32_e32 v82, v115, v115
	v_max_f32_e32 v83, v114, v114
	v_max_f32_e32 v82, v83, v82
	v_max3_f32 v83, v116, v117, v99
	v_max3_f32 v82, v82, v98, v100
	v_max3_f32 v82, v82, v101, v118
	v_max3_f32 v83, v83, v120, v121
	s_waitcnt lgkmcnt(4)
	v_mfma_f32_32x32x16_bf16 v[2:17], v[86:89], v[218:221], v[2:17]
	v_max3_f32 v82, v82, v119, v102
	v_max3_f32 v83, v83, v104, v105
	v_max3_f32 v82, v82, v103, v122
	v_max3_f32 v83, v83, v124, v125
	v_max3_f32 v82, v82, v123, v106
	v_max3_f32 v83, v83, v108, v109
	v_max3_f32 v82, v82, v107, v126
	s_waitcnt lgkmcnt(2)
	v_mfma_f32_32x32x16_bf16 v[2:17], v[90:93], v[222:225], v[2:17]
	v_max3_f32 v83, v83, v128, v129
	v_max3_f32 v82, v82, v127, v110
	v_max3_f32 v83, v83, v112, v113
	v_max3_f32 v82, v82, v111, v83
	v_mov_b32_e32 v83, v82
	s_nop 1
	v_permlane32_swap_b32_e32 v82, v83
	s_waitcnt lgkmcnt(0)
	v_mfma_f32_32x32x16_bf16 v[2:17], v[94:97], v[226:229], v[2:17]
	v_max_f32_e32 v83, v83, v83
	v_max_f32_e32 v82, v82, v82
	v_max_f32_e32 v82, v82, v83
	v_cmp_lt_f32_e32 vcc, s40, v82
	s_cbranch_vccnz .LBB0_113
	v_mov_b32_e32 v213, 1.0
	v_cmp_gt_f32_e32 vcc, 1.0, v213
	s_cbranch_vccz .LBB0_106

; #define SBAR() __builtin_amdgcn_sched_barrier(0)
; #define WAIT_BAR() do { asm volatile("s_waitcnt vmcnt(0)" ::: "memory"); __syncthreads(); } while (0)
; #define RESC(a) do { if (__any((a) < 1.f)) { if (hi == 0) al_l[r32] = (a); asm volatile("s_waitcnt lgkmcnt(0)" ::: "memory"); \
;     _Pragma("unroll") for (int d = 0; d < 4; ++d) _Pragma("unroll") for (int r = 0; r < 16; ++r) o[d][r] *= al_l[crow(r, hi)]; } } while (0)
; #define ROT() do { const int t_ = s_prev; s_prev = s_cur; s_cur = s_next; s_next = t_; } while (0)
; template <bool MLA>
; __device__ __forceinline__ void qkt(f32x16& p0, f32x16& p1, const char* Ks, const char* KRs, const bf16x8* qr, const char* qrl, const f32x16& negm, int r32, int hi) {
; #pragma unroll
;   for (int d0 = 0; d0 < 8; ++d0) { int cb = (d0 * 16 + hi * 8) * 2;
;     bf16x8 b0 = *reinterpret_cast<const bf16x8*>(Ks + KSWZ(r32, cb));
;     bf16x8 b1 = *reinterpret_cast<const bf16x8*>(Ks + KSWZ(32 + r32, cb));
;     if (d0 == 0) { p0 = __builtin_amdgcn_mfma_f32_32x32x16_bf16(b0, qr[0], negm, 0, 0, 0); p1 = __builtin_amdgcn_mfma_f32_32x32x16_bf16(b1, qr[0], negm, 0, 0, 0); }
;     else { p0 = __builtin_amdgcn_mfma_f32_32x32x16_bf16(b0, qr[d0], p0, 0, 0, 0); p1 = __builtin_amdgcn_mfma_f32_32x32x16_bf16(b1, qr[d0], p1, 0, 0, 0); } }
;   if constexpr (MLA) {
; #pragma unroll
;     for (int d0 = 0; d0 < 4; ++d0) { int ch = d0 * 2 + hi;
;       bf16x8 b0 = *reinterpret_cast<const bf16x8*>(KRs + KRSWZ(r32, ch));
;       bf16x8 b1 = *reinterpret_cast<const bf16x8*>(KRs + KRSWZ(32 + r32, ch));
;       const bf16x8 qq = *reinterpret_cast<const bf16x8*>(qrl + d0 * 1024);
;       p0 = __builtin_amdgcn_mfma_f32_32x32x16_bf16(b0, qq, p0, 0, 0, 0);
;       p1 = __builtin_amdgcn_mfma_f32_32x32x16_bf16(b1, qq, p1, 0, 0, 0); }
;   }
; template <bool MLA> ...
;     ...
;     RESC(alB); WAIT_BAR(); ROT();
;     SBAR(); DMA_TILE(j + 2, s_next); SBAR();
;     qkt<MLA>(pA0, pA1, K_lds + s_cur * SHM_K, KR_lds + s_cur * SHM_KR, qr, qrl, negm, r32, hi);
;     finishSM(pB0, pB1, alB, l_reg, pa0, pa1, pa2, pa3);
;     pv_d0(o, vb0 + s_prev * SHM_V, pa0, pa1, pa2, pa3); partialSM<false, false>(pA0, pA1, negm, m_reg, alA);
;     RESC(alA); WAIT_BAR(); ROT();
.LBB0_106:
	s_waitcnt vmcnt(0)
	v_exp_f32_e32 v218, v114
	v_exp_f32_e32 v219, v115
	v_exp_f32_e32 v220, v116
	v_exp_f32_e32 v221, v117
	v_exp_f32_e32 v222, v118
	v_exp_f32_e32 v223, v119
	v_exp_f32_e32 v224, v120
	v_exp_f32_e32 v225, v121
	v_exp_f32_e32 v226, v122
	v_exp_f32_e32 v227, v123
	v_exp_f32_e32 v228, v124
	v_exp_f32_e32 v229, v125
	v_exp_f32_e32 v234, v126
	v_exp_f32_e32 v235, v127
	v_exp_f32_e32 v236, v128
	v_exp_f32_e32 v237, v129
	s_waitcnt vmcnt(0)
	s_barrier
	s_add_i32 s31, s19, s31
	v_add_u32_e32 v82, s27, v210
	ds_read_b128 v[176:179], v82 offset:57344
	ds_read_b128 v[82:85], v82 offset:49152
	v_add_u32_e32 v180, s27, v209
	s_add_i32 s2, s30, 0
	s_add_i32 s2, s2, 0x18000
	s_add_u32 vcc_lo, s28, s48
	s_addc_u32 vcc_hi, s29, s49
	s_add_i32 m0, s31, 0xc000
	v_lshl_add_u64 v[250:251], v[172:173], 0, vcc
	global_load_lds_dwordx4 v[250:251], off
	v_exp_f32_e32 v238, v100
	v_add_f32_e32 v255, 0, v218
	v_add_f32_e32 v255, v219, v255
	s_waitcnt lgkmcnt(0)
	v_mfma_f32_32x32x16_bf16 v[114:129], v[82:85], v[158:161], v[66:81]
	v_exp_f32_e32 v239, v101
	v_add_f32_e32 v255, v220, v255
	v_add_f32_e32 v255, v221, v255
	v_mfma_f32_32x32x16_bf16 v[82:97], v[176:179], v[158:161], v[66:81]
	ds_read_b128 v[176:179], v180 offset:57344
	ds_read_b128 v[180:183], v180 offset:49152
	s_add_u32 vcc_lo, s28, 0x43c0100
	s_addc_u32 vcc_hi, s29, 0
	s_mov_b32 m0, s31
	v_lshl_add_u64 v[250:251], v[170:171], 0, vcc
	global_load_lds_dwordx4 v[250:251], off
	v_exp_f32_e32 v246, v102
	v_add_f32_e32 v255, v222, v255
	v_add_f32_e32 v255, v223, v255
	s_waitcnt lgkmcnt(0)
	v_mfma_f32_32x32x16_bf16 v[114:129], v[180:183], v[154:157], v[114:129]
	v_exp_f32_e32 v247, v103
	v_add_f32_e32 v255, v224, v255
	v_add_f32_e32 v255, v225, v255
	v_add_u32_e32 v180, s27, v208
	v_mfma_f32_32x32x16_bf16 v[82:97], v[176:179], v[154:157], v[82:97]
	ds_read_b128 v[176:179], v180 offset:57344
	ds_read_b128 v[180:183], v180 offset:49152
	s_add_u32 vcc_lo, s28, s48
	s_addc_u32 vcc_hi, s29, s49
	s_add_i32 m0, s31, 0xc400
	v_lshl_add_u64 v[250:251], v[174:175], 0, vcc
	global_load_lds_dwordx4 v[250:251], off
	v_exp_f32_e32 v249, v104
	v_add_f32_e32 v255, v226, v255
	v_add_f32_e32 v255, v227, v255
	s_waitcnt lgkmcnt(0)
	v_mfma_f32_32x32x16_bf16 v[114:129], v[180:183], v[150:153], v[114:129]
	v_exp_f32_e32 v252, v105
	v_add_f32_e32 v255, v228, v255
	v_add_f32_e32 v255, v229, v255
	v_add_u32_e32 v180, s27, v207
	v_mfma_f32_32x32x16_bf16 v[82:97], v[176:179], v[150:153], v[82:97]
	ds_read_b128 v[176:179], v180 offset:57344
	ds_read_b128 v[180:183], v180 offset:49152
	s_add_u32 vcc_lo, s28, 0x43c0180
	s_addc_u32 vcc_hi, s29, 0
	s_add_i32 m0, s31, 0x400
	v_lshl_add_u64 v[250:251], v[170:171], 0, vcc
	global_load_lds_dwordx4 v[250:251], off
	v_exp_f32_e32 v253, v106
	v_add_f32_e32 v255, v234, v255
	v_add_f32_e32 v255, v235, v255
	s_waitcnt lgkmcnt(0)
	v_mfma_f32_32x32x16_bf16 v[114:129], v[180:183], v[146:149], v[114:129]
	v_exp_f32_e32 v254, v107
	v_add_f32_e32 v255, v236, v255
	v_add_f32_e32 v255, v237, v255
	v_add_u32_e32 v180, s27, v206
	v_mfma_f32_32x32x16_bf16 v[82:97], v[176:179], v[146:149], v[82:97]
	ds_read_b128 v[176:179], v180 offset:57344
	ds_read_b128 v[180:183], v180 offset:49152
	s_lshl_b32 s32, s24, 13
	s_add_u32 vcc_lo, s28, 0x2e360600
	s_addc_u32 vcc_hi, s29, 0
	s_add_i32 m0, s23, s32
	v_lshl_add_u64 v[250:251], v[168:169], 0, vcc
	global_load_lds_dwordx4 v[250:251], off
	v_cvt_pk_bf16_f32 v100, v218, v219
	v_exp_f32_e32 v98, v98
	s_waitcnt lgkmcnt(0)
	v_mfma_f32_32x32x16_bf16 v[114:129], v[180:183], v[142:145], v[114:129]
	v_cvt_pk_bf16_f32 v101, v220, v221
	v_exp_f32_e32 v99, v99
	v_add_u32_e32 v180, s27, v205
	v_mfma_f32_32x32x16_bf16 v[82:97], v[176:179], v[142:145], v[82:97]
	ds_read_b128 v[176:179], v180 offset:57344
	ds_read_b128 v[180:183], v180 offset:49152
	v_cvt_pk_bf16_f32 v102, v222, v223
	v_exp_f32_e32 v108, v108
	s_waitcnt lgkmcnt(0)
	v_mfma_f32_32x32x16_bf16 v[114:129], v[180:183], v[138:141], v[114:129]
	v_cvt_pk_bf16_f32 v103, v224, v225
	v_exp_f32_e32 v109, v109
	v_add_u32_e32 v180, s27, v204
	v_mfma_f32_32x32x16_bf16 v[82:97], v[176:179], v[138:141], v[82:97]
	ds_read_b128 v[176:179], v180 offset:57344
	ds_read_b128 v[180:183], v180 offset:49152
	v_cvt_pk_bf16_f32 v104, v226, v227
	v_exp_f32_e32 v110, v110
	s_waitcnt lgkmcnt(0)
	v_mfma_f32_32x32x16_bf16 v[114:129], v[180:183], v[134:137], v[114:129]
	v_cvt_pk_bf16_f32 v105, v228, v229
	v_exp_f32_e32 v111, v111
	v_add_u32_e32 v180, s27, v203
	v_mfma_f32_32x32x16_bf16 v[82:97], v[176:179], v[134:137], v[82:97]
	ds_read_b128 v[176:179], v180 offset:57344
	ds_read_b128 v[180:183], v180 offset:49152
	v_cvt_pk_bf16_f32 v106, v234, v235
	v_exp_f32_e32 v112, v112
	s_waitcnt lgkmcnt(0)
	v_mfma_f32_32x32x16_bf16 v[114:129], v[180:183], v[130:133], v[114:129]
	v_cvt_pk_bf16_f32 v107, v236, v237
	v_exp_f32_e32 v113, v113
	v_add_u32_e32 v180, s2, v200
	v_mfma_f32_32x32x16_bf16 v[82:97], v[176:179], v[130:133], v[82:97]
	ds_read_b128 v[176:179], v180
	ds_read_b128 v[180:183], v180 offset:4096
	ds_read_b128 v[214:217], v198
	v_add_f32_e32 v255, v98, v255
	v_add_f32_e32 v255, v99, v255
	s_waitcnt lgkmcnt(0)
	v_mfma_f32_32x32x16_bf16 v[114:129], v[176:179], v[214:217], v[114:129]
	v_add_f32_e32 v255, v238, v255
	v_add_f32_e32 v255, v239, v255
	v_mfma_f32_32x32x16_bf16 v[82:97], v[180:183], v[214:217], v[82:97]
	v_add_u32_e32 v180, s2, v201
	ds_read_b128 v[176:179], v180
	ds_read_b128 v[180:183], v180 offset:4096
	ds_read_b128 v[214:217], v198 offset:1024
	v_add_f32_e32 v255, v246, v255
	v_add_f32_e32 v255, v247, v255
	s_waitcnt lgkmcnt(0)
; #define SBAR() __builtin_amdgcn_sched_barrier(0)
; __device__ __forceinline__ void finishSM(f32x16& p0, f32x16& p1, float alpha, float& l_reg, bf16x8& pa0, bf16x8& pa1, bf16x8& pa2, bf16x8& pa3) {
; #pragma unroll
;   for (int r = 0; r < 16; ++r) p1[r] = __builtin_amdgcn_exp2f(p1[r]);
;   float ps = 0;
; #pragma unroll
;   for (int r = 0; r < 16; ++r) ps += p0[r];
; #pragma unroll
;   for (int r = 0; r < 16; ++r) ps += p1[r];
;   { auto rr = __builtin_amdgcn_permlane32_swap(__float_as_uint(ps), __float_as_uint(ps), false, false);
;     ps = __uint_as_float(rr[0]) + __uint_as_float(rr[1]); }
;   l_reg = l_reg * alpha + ps;
;     ...
;   PK4(p0, 0, pa0); PK4(p0, 8, pa1); PK4(p1, 0, pa2); PK4(p1, 8, pa3);
; template <int D0> __device__ __forceinline__ void pv_one(f32x16& od, int vb, bf16x8 pa0, bf16x8 pa1, bf16x8 pa2, bf16x8 pa3) {
;   const s16x4 l0 = tr_read<v_rd_off(D0, 0, 0)>(vb), h0 = tr_read<v_rd_off(D0, 0, 1)>(vb), l1 = tr_read<v_rd_off(D0, 1, 0)>(vb), h1 = tr_read<v_rd_off(D0, 1, 1)>(vb);
;   const s16x4 l2 = tr_read<v_rd_off(D0, 2, 0)>(vb), h2 = tr_read<v_rd_off(D0, 2, 1)>(vb), l3 = tr_read<v_rd_off(D0, 3, 0)>(vb), h3 = tr_read<v_rd_off(D0, 3, 1)>(vb);
;   asm volatile("s_waitcnt lgkmcnt(0)" ::: "memory"); SBAR();
;     ...
;   od = __builtin_amdgcn_mfma_f32_32x32x16_bf16(pa0, PK(l0, h0), od, 0, 0, 0);
;   od = __builtin_amdgcn_mfma_f32_32x32x16_bf16(pa1, PK(l1, h1), od, 0, 0, 0);
;   od = __builtin_amdgcn_mfma_f32_32x32x16_bf16(pa2, PK(l2, h2), od, 0, 0, 0);
;   od = __builtin_amdgcn_mfma_f32_32x32x16_bf16(pa3, PK(l3, h3), od, 0, 0, 0);
;     ...
; }
; __device__ __forceinline__ void pv_d0(f32x16* o, int vb, bf16x8 pa0, bf16x8 pa1, bf16x8 pa2, bf16x8 pa3) {
;   pv_one<0>(o[0], vb, pa0, pa1, pa2, pa3); pv_one<1>(o[1], vb, pa0, pa1, pa2, pa3); pv_one<2>(o[2], vb, pa0, pa1, pa2, pa3); pv_one<3>(o[3], vb, pa0, pa1, pa2, pa3);
	v_mfma_f32_32x32x16_bf16 v[114:129], v[176:179], v[214:217], v[114:129]
	v_add_f32_e32 v255, v249, v255
	v_add_f32_e32 v255, v252, v255
	v_mfma_f32_32x32x16_bf16 v[82:97], v[180:183], v[214:217], v[82:97]
	v_add_u32_e32 v180, s2, v199
	ds_read_b128 v[176:179], v180
	ds_read_b128 v[180:183], v180 offset:4096
	ds_read_b128 v[214:217], v198 offset:2048
	v_add_f32_e32 v255, v253, v255
	v_add_f32_e32 v255, v254, v255
	s_waitcnt lgkmcnt(0)
	v_mfma_f32_32x32x16_bf16 v[114:129], v[176:179], v[214:217], v[114:129]
	v_add_f32_e32 v255, v108, v255
	v_add_f32_e32 v255, v109, v255
	v_mfma_f32_32x32x16_bf16 v[82:97], v[180:183], v[214:217], v[82:97]
	v_add_u32_e32 v180, s2, v202
	ds_read_b128 v[176:179], v180
	ds_read_b128 v[180:183], v180 offset:4096
	ds_read_b128 v[214:217], v198 offset:3072
	v_add_f32_e32 v255, v110, v255
	v_add_f32_e32 v255, v111, v255
	s_waitcnt lgkmcnt(0)
	v_mfma_f32_32x32x16_bf16 v[114:129], v[176:179], v[214:217], v[114:129]
	v_add_f32_e32 v255, v112, v255
	v_add_f32_e32 v255, v113, v255
	v_mfma_f32_32x32x16_bf16 v[82:97], v[180:183], v[214:217], v[82:97]
	v_cvt_pk_bf16_f32 v176, v253, v254
	v_cvt_pk_bf16_f32 v177, v108, v109
	v_cvt_pk_bf16_f32 v178, v110, v111
	v_cvt_pk_bf16_f32 v179, v112, v113
	v_cvt_pk_bf16_f32 v108, v98, v99
	v_cvt_pk_bf16_f32 v109, v238, v239
	v_cvt_pk_bf16_f32 v110, v246, v247
	v_cvt_pk_bf16_f32 v111, v249, v252
	v_mov_b32_e32 v98, v255
	v_add_u32_e32 v112, s11, v197
	ds_read_b64_tr_b16 v[180:181], v112 offset:0
	ds_read_b64_tr_b16 v[182:183], v112 offset:0x800
	ds_read_b64_tr_b16 v[214:215], v112 offset:0x1000
	ds_read_b64_tr_b16 v[216:217], v112 offset:0x1800
	ds_read_b64_tr_b16 v[218:219], v112 offset:0x2000
	ds_read_b64_tr_b16 v[220:221], v112 offset:0x2800
	ds_read_b64_tr_b16 v[222:223], v112 offset:0x3000
	ds_read_b64_tr_b16 v[224:225], v112 offset:0x3800
	v_mov_b32_e32 v99, v98
	s_nop 1
	v_permlane32_swap_b32_e32 v98, v99
	v_permlane32_swap_b32_e32 v100, v102
	v_permlane32_swap_b32_e32 v176, v178
	v_permlane32_swap_b32_e32 v101, v103
	v_permlane32_swap_b32_e32 v104, v106
	v_permlane32_swap_b32_e32 v105, v107
	v_permlane32_swap_b32_e32 v108, v110
	v_permlane32_swap_b32_e32 v109, v111
	v_permlane32_swap_b32_e32 v177, v179
	s_waitcnt lgkmcnt(6)
	v_mfma_f32_32x32x16_bf16 v[50:65], v[100:103], v[180:183], v[50:65]
	ds_read_b64_tr_b16 v[180:181], v112 offset:0x200
	ds_read_b64_tr_b16 v[182:183], v112 offset:0xa00
	s_waitcnt lgkmcnt(6)
	v_mfma_f32_32x32x16_bf16 v[50:65], v[104:107], v[214:217], v[50:65]
	ds_read_b64_tr_b16 v[214:215], v112 offset:0x1200
	ds_read_b64_tr_b16 v[216:217], v112 offset:0x1a00
	s_waitcnt lgkmcnt(6)
	v_mfma_f32_32x32x16_bf16 v[50:65], v[108:111], v[218:221], v[50:65]
	ds_read_b64_tr_b16 v[218:219], v112 offset:0x2200
	ds_read_b64_tr_b16 v[220:221], v112 offset:0x2a00
	s_waitcnt lgkmcnt(6)
	v_mfma_f32_32x32x16_bf16 v[50:65], v[176:179], v[222:225], v[50:65]
	ds_read_b64_tr_b16 v[222:223], v112 offset:0x3200
	ds_read_b64_tr_b16 v[224:225], v112 offset:0x3a00
	s_waitcnt lgkmcnt(6)
	v_mfma_f32_32x32x16_bf16 v[34:49], v[100:103], v[180:183], v[34:49]
	ds_read_b64_tr_b16 v[180:181], v112 offset:0x400
	ds_read_b64_tr_b16 v[182:183], v112 offset:0xc00
	s_waitcnt lgkmcnt(6)
	v_mfma_f32_32x32x16_bf16 v[34:49], v[104:107], v[214:217], v[34:49]
	ds_read_b64_tr_b16 v[214:215], v112 offset:0x1400
	ds_read_b64_tr_b16 v[216:217], v112 offset:0x1c00
	s_waitcnt lgkmcnt(6)
	v_mfma_f32_32x32x16_bf16 v[34:49], v[108:111], v[218:221], v[34:49]
	ds_read_b64_tr_b16 v[218:219], v112 offset:0x2400
	ds_read_b64_tr_b16 v[220:221], v112 offset:0x2c00
	s_waitcnt lgkmcnt(6)
	v_mfma_f32_32x32x16_bf16 v[34:49], v[176:179], v[222:225], v[34:49]
	ds_read_b64_tr_b16 v[222:223], v112 offset:0x3400
	ds_read_b64_tr_b16 v[224:225], v112 offset:0x3c00
	s_waitcnt lgkmcnt(6)
	v_mfma_f32_32x32x16_bf16 v[18:33], v[100:103], v[180:183], v[18:33]
	ds_read_b64_tr_b16 v[180:181], v112 offset:0x600
	ds_read_b64_tr_b16 v[182:183], v112 offset:0xe00
	s_waitcnt lgkmcnt(6)
	v_mfma_f32_32x32x16_bf16 v[18:33], v[104:107], v[214:217], v[18:33]
	ds_read_b64_tr_b16 v[214:215], v112 offset:0x1600
	ds_read_b64_tr_b16 v[216:217], v112 offset:0x1e00
	s_waitcnt lgkmcnt(6)
	v_mfma_f32_32x32x16_bf16 v[18:33], v[108:111], v[218:221], v[18:33]
	ds_read_b64_tr_b16 v[218:219], v112 offset:0x2600
	ds_read_b64_tr_b16 v[220:221], v112 offset:0x2e00
	s_waitcnt lgkmcnt(6)
	v_mfma_f32_32x32x16_bf16 v[18:33], v[176:179], v[222:225], v[18:33]
	ds_read_b64_tr_b16 v[222:223], v112 offset:0x3600
	ds_read_b64_tr_b16 v[224:225], v112 offset:0x3e00
	s_waitcnt lgkmcnt(6)
	v_mfma_f32_32x32x16_bf16 v[2:17], v[100:103], v[180:183], v[2:17]
	v_max_f32_e32 v100, v115, v115
	v_max_f32_e32 v101, v114, v114
	v_max_f32_e32 v100, v101, v100
	v_max3_f32 v101, v116, v117, v83
	v_max3_f32 v100, v100, v82, v84
	v_max3_f32 v100, v100, v85, v118
	v_max3_f32 v101, v101, v120, v121
	s_waitcnt lgkmcnt(4)
	v_mfma_f32_32x32x16_bf16 v[2:17], v[104:107], v[214:217], v[2:17]
	v_max3_f32 v100, v100, v119, v86
	v_max3_f32 v101, v101, v88, v89
	v_max3_f32 v100, v100, v87, v122
	v_max3_f32 v101, v101, v124, v125
	v_max3_f32 v100, v100, v123, v90
	v_max3_f32 v101, v101, v92, v93
	v_max3_f32 v100, v100, v91, v126
	s_waitcnt lgkmcnt(2)
	v_mfma_f32_32x32x16_bf16 v[2:17], v[108:111], v[218:221], v[2:17]
	v_max3_f32 v101, v101, v128, v129
	v_max3_f32 v100, v100, v127, v94
	v_max3_f32 v101, v101, v96, v97
	v_max3_f32 v100, v100, v95, v101
	v_mov_b32_e32 v101, v100
	s_nop 1
	v_permlane32_swap_b32_e32 v100, v101
	s_waitcnt lgkmcnt(0)
	v_mfma_f32_32x32x16_bf16 v[2:17], v[176:179], v[222:225], v[2:17]
	v_max_f32_e32 v101, v101, v101
	v_max_f32_e32 v100, v100, v100
	v_max_f32_e32 v100, v100, v101
	v_cmp_lt_f32_e32 vcc, s40, v100
	v_mov_b32_e32 v176, 1.0
	s_cbranch_vccnz .LBB0_114
	v_cmp_gt_f32_e32 vcc, 1.0, v176
	s_cbranch_vccz .LBB0_111

; template <bool MLA>
; __device__ __forceinline__ void qkt(f32x16& p0, f32x16& p1, const char* Ks, const char* KRs, const bf16x8* qr, const char* qrl, const f32x16& negm, int r32, int hi) {
; #pragma unroll
;   for (int d0 = 0; d0 < 8; ++d0) { int cb = (d0 * 16 + hi * 8) * 2;
;     bf16x8 b0 = *reinterpret_cast<const bf16x8*>(Ks + KSWZ(r32, cb));
;     bf16x8 b1 = *reinterpret_cast<const bf16x8*>(Ks + KSWZ(32 + r32, cb));
;     if (d0 == 0) { p0 = __builtin_amdgcn_mfma_f32_32x32x16_bf16(b0, qr[0], negm, 0, 0, 0); p1 = __builtin_amdgcn_mfma_f32_32x32x16_bf16(b1, qr[0], negm, 0, 0, 0); }
;     else { p0 = __builtin_amdgcn_mfma_f32_32x32x16_bf16(b0, qr[d0], p0, 0, 0, 0); p1 = __builtin_amdgcn_mfma_f32_32x32x16_bf16(b1, qr[d0], p1, 0, 0, 0); } }
.LBB0_125:
	s_mov_b32 s13, s16
	s_mov_b32 s16, s23
	s_lshl_b32 s8, s17, 14
	s_add_i32 s23, s8, 0
	s_add_i32 s32, s23, s14
	s_lshl_b32 s19, s13, 14
	s_add_i32 s8, s19, 0
	v_add_u32_e32 v98, s8, v199
	ds_read_b128 v[220:223], v98 offset:57344
	ds_read_b128 v[98:101], v98 offset:49152
	v_add_u32_e32 v201, s8, v198
	s_add_u32 vcc_lo, s2, s62
	s_addc_u32 vcc_hi, s3, s63
	s_add_i32 m0, s32, 0xc000
	v_lshl_add_u64 v[250:251], v[168:169], 0, vcc
	global_load_lds_dwordx4 v[250:251], off
	v_exp_f32_e32 v203, v82
	v_add_f32_e32 v82, 0, v217
	v_add_f32_e32 v82, v219, v82
	s_waitcnt lgkmcnt(0)
	v_mfma_f32_32x32x16_bf16 v[114:129], v[98:101], v[158:161], v[66:81]
	v_add_f32_e32 v82, v215, v82
	v_add_f32_e32 v82, v218, v82
	v_add_f32_e32 v82, v214, v82
	v_add_f32_e32 v82, v216, v82
	v_add_f32_e32 v82, v212, v82
	v_add_f32_e32 v82, v213, v82
	v_add_f32_e32 v82, v209, v82
	v_mfma_f32_32x32x16_bf16 v[98:113], v[220:223], v[158:161], v[66:81]
	ds_read_b128 v[220:223], v201 offset:57344
	ds_read_b128 v[224:227], v201 offset:49152
	v_add_u32_e32 v201, s8, v197
	s_add_u32 vcc_lo, s2, 0x1c3c1600
	s_addc_u32 vcc_hi, s3, 0
	s_mov_b32 m0, s32
	v_lshl_add_u64 v[250:251], v[0:1], 0, vcc
	global_load_lds_dwordx4 v[250:251], off
	v_add_f32_e32 v82, v211, v82
	v_add_f32_e32 v82, v208, v82
	v_add_f32_e32 v82, v210, v82
	v_add_f32_e32 v82, v205, v82
	v_add_f32_e32 v82, v207, v82
	s_waitcnt lgkmcnt(0)
	v_mfma_f32_32x32x16_bf16 v[98:113], v[220:223], v[154:157], v[98:113]
	v_add_f32_e32 v82, v204, v82
	v_add_f32_e32 v82, v206, v82
	v_add_f32_e32 v82, v203, v82
	v_exp_f32_e32 v228, v91
	v_exp_f32_e32 v229, v92
	v_exp_f32_e32 v234, v93
	v_exp_f32_e32 v235, v94
	v_mfma_f32_32x32x16_bf16 v[114:129], v[224:227], v[154:157], v[114:129]
	ds_read_b128 v[220:223], v201 offset:57344
	ds_read_b128 v[224:227], v201 offset:49152
	v_add_u32_e32 v201, s8, v196
	s_add_u32 vcc_lo, s2, s62
	s_addc_u32 vcc_hi, s3, s63
	s_add_i32 m0, s32, 0xc400
	v_lshl_add_u64 v[250:251], v[170:171], 0, vcc
	global_load_lds_dwordx4 v[250:251], off
	v_exp_f32_e32 v236, v95
	v_exp_f32_e32 v237, v96
	v_exp_f32_e32 v97, v97
	s_lshl_b32 s24, s16, 14
	s_waitcnt lgkmcnt(0)
	v_mfma_f32_32x32x16_bf16 v[98:113], v[220:223], v[150:153], v[98:113]
	v_mfma_f32_32x32x16_bf16 v[114:129], v[224:227], v[150:153], v[114:129]
	ds_read_b128 v[220:223], v201 offset:57344
	ds_read_b128 v[224:227], v201 offset:49152
	v_add_u32_e32 v201, s8, v195
	s_add_u32 vcc_lo, s2, 0x1c3c1680
	s_addc_u32 vcc_hi, s3, 0
	s_add_i32 m0, s32, 0x400
	v_lshl_add_u64 v[250:251], v[0:1], 0, vcc
	global_load_lds_dwordx4 v[250:251], off
	s_waitcnt lgkmcnt(0)
	v_mfma_f32_32x32x16_bf16 v[98:113], v[220:223], v[146:149], v[98:113]
	v_mfma_f32_32x32x16_bf16 v[114:129], v[224:227], v[146:149], v[114:129]
	ds_read_b128 v[220:223], v201 offset:57344
	ds_read_b128 v[224:227], v201 offset:49152
	v_add_u32_e32 v201, s8, v183
	s_waitcnt lgkmcnt(0)
	v_mfma_f32_32x32x16_bf16 v[98:113], v[220:223], v[142:145], v[98:113]
	v_mfma_f32_32x32x16_bf16 v[114:129], v[224:227], v[142:145], v[114:129]
	ds_read_b128 v[220:223], v201 offset:57344
	ds_read_b128 v[224:227], v201 offset:49152
	v_add_u32_e32 v201, s8, v193
	s_waitcnt lgkmcnt(0)
	v_mfma_f32_32x32x16_bf16 v[98:113], v[220:223], v[138:141], v[98:113]
	v_mfma_f32_32x32x16_bf16 v[114:129], v[224:227], v[138:141], v[114:129]
	ds_read_b128 v[220:223], v201 offset:57344
	ds_read_b128 v[224:227], v201 offset:49152
	v_add_u32_e32 v201, s8, v194
	s_waitcnt lgkmcnt(0)
	v_mfma_f32_32x32x16_bf16 v[98:113], v[220:223], v[134:137], v[98:113]
	v_mfma_f32_32x32x16_bf16 v[114:129], v[224:227], v[134:137], v[114:129]
	ds_read_b128 v[220:223], v201 offset:57344
	ds_read_b128 v[224:227], v201 offset:49152
	s_waitcnt lgkmcnt(0)
; #define SBAR() __builtin_amdgcn_sched_barrier(0)
; __device__ __forceinline__ void finishSM(f32x16& p0, f32x16& p1, float alpha, float& l_reg, bf16x8& pa0, bf16x8& pa1, bf16x8& pa2, bf16x8& pa3) {
; #pragma unroll
;   for (int r = 0; r < 16; ++r) p1[r] = __builtin_amdgcn_exp2f(p1[r]);
;   float ps = 0;
; #pragma unroll
;   for (int r = 0; r < 16; ++r) ps += p0[r];
; #pragma unroll
;   for (int r = 0; r < 16; ++r) ps += p1[r];
;   { auto rr = __builtin_amdgcn_permlane32_swap(__float_as_uint(ps), __float_as_uint(ps), false, false);
;     ps = __uint_as_float(rr[0]) + __uint_as_float(rr[1]); }
;   l_reg = l_reg * alpha + ps;
;     ...
;   PK4(p0, 0, pa0); PK4(p0, 8, pa1); PK4(p1, 0, pa2); PK4(p1, 8, pa3);
; template <int D0> __device__ __forceinline__ void pv_one(f32x16& od, int vb, bf16x8 pa0, bf16x8 pa1, bf16x8 pa2, bf16x8 pa3) {
;   const s16x4 l0 = tr_read<v_rd_off(D0, 0, 0)>(vb), h0 = tr_read<v_rd_off(D0, 0, 1)>(vb), l1 = tr_read<v_rd_off(D0, 1, 0)>(vb), h1 = tr_read<v_rd_off(D0, 1, 1)>(vb);
;   const s16x4 l2 = tr_read<v_rd_off(D0, 2, 0)>(vb), h2 = tr_read<v_rd_off(D0, 2, 1)>(vb), l3 = tr_read<v_rd_off(D0, 3, 0)>(vb), h3 = tr_read<v_rd_off(D0, 3, 1)>(vb);
;   asm volatile("s_waitcnt lgkmcnt(0)" ::: "memory"); SBAR();
;     ...
;   od = __builtin_amdgcn_mfma_f32_32x32x16_bf16(pa0, PK(l0, h0), od, 0, 0, 0);
;   od = __builtin_amdgcn_mfma_f32_32x32x16_bf16(pa1, PK(l1, h1), od, 0, 0, 0);
;   od = __builtin_amdgcn_mfma_f32_32x32x16_bf16(pa2, PK(l2, h2), od, 0, 0, 0);
;   od = __builtin_amdgcn_mfma_f32_32x32x16_bf16(pa3, PK(l3, h3), od, 0, 0, 0);
;     ...
; }
; __device__ __forceinline__ void pv_d0(f32x16* o, int vb, bf16x8 pa0, bf16x8 pa1, bf16x8 pa2, bf16x8 pa3) {
;   pv_one<0>(o[0], vb, pa0, pa1, pa2, pa3); pv_one<1>(o[1], vb, pa0, pa1, pa2, pa3); pv_one<2>(o[2], vb, pa0, pa1, pa2, pa3); pv_one<3>(o[3], vb, pa0, pa1, pa2, pa3);
	v_mfma_f32_32x32x16_bf16 v[98:113], v[220:223], v[130:133], v[98:113]
	v_exp_f32_e32 v220, v83
	v_exp_f32_e32 v221, v84
	v_exp_f32_e32 v222, v85
	v_exp_f32_e32 v223, v86
	v_add_f32_e32 v82, v220, v82
	v_add_f32_e32 v82, v221, v82
	v_add_f32_e32 v82, v222, v82
	v_mfma_f32_32x32x16_bf16 v[114:129], v[224:227], v[130:133], v[114:129]
	v_exp_f32_e32 v224, v87
	v_exp_f32_e32 v225, v88
	v_exp_f32_e32 v226, v89
	v_exp_f32_e32 v227, v90
	v_add_f32_e32 v82, v223, v82
	v_add_f32_e32 v82, v224, v82
	v_add_f32_e32 v82, v225, v82
	v_add_f32_e32 v82, v226, v82
	v_add_f32_e32 v82, v227, v82
	v_add_f32_e32 v82, v228, v82
	v_add_f32_e32 v82, v229, v82
	v_add_f32_e32 v82, v234, v82
	v_add_f32_e32 v82, v235, v82
	v_add_f32_e32 v82, v236, v82
	v_add_f32_e32 v82, v237, v82
	v_add_f32_e32 v201, v97, v82
	v_cvt_pk_bf16_f32 v82, v217, v219
	v_cvt_pk_bf16_f32 v83, v215, v218
	v_cvt_pk_bf16_f32 v84, v214, v216
	v_cvt_pk_bf16_f32 v85, v212, v213
	v_cvt_pk_bf16_f32 v86, v209, v211
	v_cvt_pk_bf16_f32 v87, v208, v210
	v_cvt_pk_bf16_f32 v88, v205, v207
	v_cvt_pk_bf16_f32 v89, v204, v206
	v_cvt_pk_bf16_f32 v90, v203, v220
	v_cvt_pk_bf16_f32 v91, v221, v222
	v_cvt_pk_bf16_f32 v92, v223, v224
	v_cvt_pk_bf16_f32 v93, v225, v226
	v_cvt_pk_bf16_f32 v94, v227, v228
	v_cvt_pk_bf16_f32 v95, v229, v234
	v_cvt_pk_bf16_f32 v96, v235, v236
	v_cvt_pk_bf16_f32 v97, v237, v97
	v_add_u32_e32 v203, s24, v182
	ds_read_b64_tr_b16 v[204:205], v203 offset:0
	ds_read_b64_tr_b16 v[206:207], v203 offset:0x800
	ds_read_b64_tr_b16 v[208:209], v203 offset:0x1000
	ds_read_b64_tr_b16 v[210:211], v203 offset:0x1800
	ds_read_b64_tr_b16 v[212:213], v203 offset:0x2000
	ds_read_b64_tr_b16 v[214:215], v203 offset:0x2800
	ds_read_b64_tr_b16 v[216:217], v203 offset:0x3000
	ds_read_b64_tr_b16 v[218:219], v203 offset:0x3800
	v_mov_b32_e32 v202, v201
	s_nop 1
	v_permlane32_swap_b32_e32 v201, v202
	v_permlane32_swap_b32_e32 v82, v84
	v_permlane32_swap_b32_e32 v83, v85
	v_permlane32_swap_b32_e32 v86, v88
	v_permlane32_swap_b32_e32 v87, v89
	v_permlane32_swap_b32_e32 v90, v92
	v_permlane32_swap_b32_e32 v91, v93
	v_permlane32_swap_b32_e32 v94, v96
	v_permlane32_swap_b32_e32 v95, v97
	s_waitcnt lgkmcnt(6)
	v_mfma_f32_32x32x16_bf16 v[2:17], v[82:85], v[204:207], v[2:17]
	ds_read_b64_tr_b16 v[204:205], v203 offset:0x200
	ds_read_b64_tr_b16 v[206:207], v203 offset:0xa00
	s_waitcnt lgkmcnt(6)
	v_mfma_f32_32x32x16_bf16 v[2:17], v[86:89], v[208:211], v[2:17]
	ds_read_b64_tr_b16 v[208:209], v203 offset:0x1200
	ds_read_b64_tr_b16 v[210:211], v203 offset:0x1a00
	s_waitcnt lgkmcnt(6)
	v_mfma_f32_32x32x16_bf16 v[2:17], v[90:93], v[212:215], v[2:17]
	ds_read_b64_tr_b16 v[212:213], v203 offset:0x2200
	ds_read_b64_tr_b16 v[214:215], v203 offset:0x2a00
	s_waitcnt lgkmcnt(6)
	v_mfma_f32_32x32x16_bf16 v[2:17], v[94:97], v[216:219], v[2:17]
	ds_read_b64_tr_b16 v[216:217], v203 offset:0x3200
	ds_read_b64_tr_b16 v[218:219], v203 offset:0x3a00
	s_waitcnt lgkmcnt(6)
	v_mfma_f32_32x32x16_bf16 v[50:65], v[82:85], v[204:207], v[50:65]
	ds_read_b64_tr_b16 v[204:205], v203 offset:0x400
	ds_read_b64_tr_b16 v[206:207], v203 offset:0xc00
	s_waitcnt lgkmcnt(6)
	v_mfma_f32_32x32x16_bf16 v[50:65], v[86:89], v[208:211], v[50:65]
	ds_read_b64_tr_b16 v[208:209], v203 offset:0x1400
	ds_read_b64_tr_b16 v[210:211], v203 offset:0x1c00
	s_waitcnt lgkmcnt(6)
	v_mfma_f32_32x32x16_bf16 v[50:65], v[90:93], v[212:215], v[50:65]
	ds_read_b64_tr_b16 v[212:213], v203 offset:0x2400
	ds_read_b64_tr_b16 v[214:215], v203 offset:0x2c00
	s_waitcnt lgkmcnt(6)
	v_mfma_f32_32x32x16_bf16 v[50:65], v[94:97], v[216:219], v[50:65]
	ds_read_b64_tr_b16 v[216:217], v203 offset:0x3400
	ds_read_b64_tr_b16 v[218:219], v203 offset:0x3c00
	s_waitcnt lgkmcnt(6)
	v_mfma_f32_32x32x16_bf16 v[34:49], v[82:85], v[204:207], v[34:49]
	ds_read_b64_tr_b16 v[204:205], v203 offset:0x600
	ds_read_b64_tr_b16 v[206:207], v203 offset:0xe00
	s_waitcnt lgkmcnt(6)
	v_mfma_f32_32x32x16_bf16 v[34:49], v[86:89], v[208:211], v[34:49]
	ds_read_b64_tr_b16 v[208:209], v203 offset:0x1600
	ds_read_b64_tr_b16 v[210:211], v203 offset:0x1e00
	s_waitcnt lgkmcnt(6)
	v_mfma_f32_32x32x16_bf16 v[34:49], v[90:93], v[212:215], v[34:49]
	ds_read_b64_tr_b16 v[212:213], v203 offset:0x2600
	ds_read_b64_tr_b16 v[214:215], v203 offset:0x2e00
	s_waitcnt lgkmcnt(6)
	v_mfma_f32_32x32x16_bf16 v[34:49], v[94:97], v[216:219], v[34:49]
	ds_read_b64_tr_b16 v[216:217], v203 offset:0x3600
	ds_read_b64_tr_b16 v[218:219], v203 offset:0x3e00
	s_waitcnt lgkmcnt(6)
	v_mfma_f32_32x32x16_bf16 v[18:33], v[82:85], v[204:207], v[18:33]
	v_max_f32_e32 v82, v115, v115
	v_max_f32_e32 v83, v114, v114
	v_max_f32_e32 v82, v83, v82
	v_max3_f32 v83, v116, v117, v99
	v_max3_f32 v82, v82, v98, v100
	v_max3_f32 v82, v82, v101, v118
	v_max3_f32 v83, v83, v120, v121
	s_waitcnt lgkmcnt(4)
	v_mfma_f32_32x32x16_bf16 v[18:33], v[86:89], v[208:211], v[18:33]
	v_max3_f32 v82, v82, v119, v102
	v_max3_f32 v83, v83, v104, v105
	v_max3_f32 v82, v82, v103, v122
	v_max3_f32 v83, v83, v124, v125
	v_max3_f32 v82, v82, v123, v106
	v_max3_f32 v83, v83, v108, v109
	v_max3_f32 v82, v82, v107, v126
	s_waitcnt lgkmcnt(2)
	v_mfma_f32_32x32x16_bf16 v[18:33], v[90:93], v[212:215], v[18:33]
	v_max3_f32 v83, v83, v128, v129
	v_max3_f32 v82, v82, v127, v110
	v_max3_f32 v83, v83, v112, v113
	v_max3_f32 v82, v82, v111, v83
	v_mov_b32_e32 v83, v82
	s_nop 1
	v_permlane32_swap_b32_e32 v82, v83
	s_waitcnt lgkmcnt(0)
	v_mfma_f32_32x32x16_bf16 v[18:33], v[94:97], v[216:219], v[18:33]
	v_max_f32_e32 v83, v83, v83
	v_max_f32_e32 v82, v82, v82
	v_max_f32_e32 v82, v82, v83
	v_cmp_lt_f32_e32 vcc, s40, v82
	s_cbranch_vccnz .LBB0_137
	v_mov_b32_e32 v203, 1.0
	v_cmp_gt_f32_e32 vcc, 1.0, v203
	s_cbranch_vccz .LBB0_130

; #define SBAR() __builtin_amdgcn_sched_barrier(0)
; #define WAIT_BAR() do { asm volatile("s_waitcnt vmcnt(0)" ::: "memory"); __syncthreads(); } while (0)
; #define RESC(a) do { if (__any((a) < 1.f)) { if (hi == 0) al_l[r32] = (a); asm volatile("s_waitcnt lgkmcnt(0)" ::: "memory"); \
;     _Pragma("unroll") for (int d = 0; d < 4; ++d) _Pragma("unroll") for (int r = 0; r < 16; ++r) o[d][r] *= al_l[crow(r, hi)]; } } while (0)
; #define ROT() do { const int t_ = s_prev; s_prev = s_cur; s_cur = s_next; s_next = t_; } while (0)
; __device__ __forceinline__ void finishSM(f32x16& p0, f32x16& p1, float alpha, float& l_reg, bf16x8& pa0, bf16x8& pa1, bf16x8& pa2, bf16x8& pa3) {
; #pragma unroll
;   for (int r = 0; r < 16; ++r) p1[r] = __builtin_amdgcn_exp2f(p1[r]);
;   float ps = 0;
; #pragma unroll
;   for (int r = 0; r < 16; ++r) ps += p0[r];
; #pragma unroll
;   for (int r = 0; r < 16; ++r) ps += p1[r];
;   { auto rr = __builtin_amdgcn_permlane32_swap(__float_as_uint(ps), __float_as_uint(ps), false, false);
;     ps = __uint_as_float(rr[0]) + __uint_as_float(rr[1]); }
;   l_reg = l_reg * alpha + ps;
;     ...
;   PK4(p0, 0, pa0); PK4(p0, 8, pa1); PK4(p1, 0, pa2); PK4(p1, 8, pa3);
; template <bool MLA> ...
;     ...
;     RESC(alB); WAIT_BAR(); ROT();
;     SBAR(); DMA_TILE(j + 2, s_next); SBAR();
;     qkt<MLA>(pA0, pA1, K_lds + s_cur * SHM_K, KR_lds + s_cur * SHM_KR, qr, qrl, negm, r32, hi);
;     finishSM(pB0, pB1, alB, l_reg, pa0, pa1, pa2, pa3);
;     pv_d0(o, vb0 + s_prev * SHM_V, pa0, pa1, pa2, pa3); partialSM<false, false>(pA0, pA1, negm, m_reg, alA);
;     RESC(alA); WAIT_BAR(); ROT();
.LBB0_130:
	s_waitcnt vmcnt(0)
	v_exp_f32_e32 v208, v114
	v_exp_f32_e32 v209, v115
	v_exp_f32_e32 v210, v116
	v_exp_f32_e32 v211, v117
	v_exp_f32_e32 v212, v118
	v_exp_f32_e32 v213, v119
	v_exp_f32_e32 v214, v120
	v_exp_f32_e32 v215, v121
	v_exp_f32_e32 v216, v122
	v_exp_f32_e32 v217, v123
	v_exp_f32_e32 v218, v124
	v_exp_f32_e32 v219, v125
	v_exp_f32_e32 v220, v126
	v_exp_f32_e32 v221, v127
	v_exp_f32_e32 v222, v128
	v_exp_f32_e32 v223, v129
	s_waitcnt vmcnt(0)
	s_barrier
	s_add_i32 s24, s15, s24
	v_add_u32_e32 v82, s23, v199
	ds_read_b128 v[172:175], v82 offset:57344
	ds_read_b128 v[82:85], v82 offset:49152
	v_add_u32_e32 v176, s23, v198
	s_add_u32 vcc_lo, s2, s74
	s_addc_u32 vcc_hi, s3, s75
	s_add_i32 m0, s24, 0xc000
	v_lshl_add_u64 v[250:251], v[168:169], 0, vcc
	global_load_lds_dwordx4 v[250:251], off
	v_exp_f32_e32 v177, v103
	v_exp_f32_e32 v224, v108
	v_exp_f32_e32 v225, v109
	s_waitcnt lgkmcnt(0)
	v_mfma_f32_32x32x16_bf16 v[114:129], v[82:85], v[158:161], v[66:81]
	v_exp_f32_e32 v226, v110
	v_exp_f32_e32 v227, v111
	v_exp_f32_e32 v112, v112
	v_exp_f32_e32 v113, v113
	v_mfma_f32_32x32x16_bf16 v[82:97], v[172:175], v[158:161], v[66:81]
	ds_read_b128 v[172:175], v176 offset:57344
	ds_read_b128 v[204:207], v176 offset:49152
	v_add_u32_e32 v176, s23, v197
	s_add_u32 vcc_lo, s2, 0x1c421600
	s_addc_u32 vcc_hi, s3, 0
	s_mov_b32 m0, s24
	v_lshl_add_u64 v[250:251], v[0:1], 0, vcc
	global_load_lds_dwordx4 v[250:251], off
	s_waitcnt lgkmcnt(0)
	v_mfma_f32_32x32x16_bf16 v[82:97], v[172:175], v[154:157], v[82:97]
	v_mfma_f32_32x32x16_bf16 v[114:129], v[204:207], v[154:157], v[114:129]
	ds_read_b128 v[172:175], v176 offset:57344
	ds_read_b128 v[204:207], v176 offset:49152
	v_add_u32_e32 v176, s23, v196
	s_add_u32 vcc_lo, s2, s74
	s_addc_u32 vcc_hi, s3, s75
	s_add_i32 m0, s24, 0xc400
	v_lshl_add_u64 v[250:251], v[170:171], 0, vcc
	global_load_lds_dwordx4 v[250:251], off
	s_waitcnt lgkmcnt(0)
	v_mfma_f32_32x32x16_bf16 v[82:97], v[172:175], v[150:153], v[82:97]
	v_mfma_f32_32x32x16_bf16 v[114:129], v[204:207], v[150:153], v[114:129]
	ds_read_b128 v[172:175], v176 offset:57344
	ds_read_b128 v[204:207], v176 offset:49152
	v_add_u32_e32 v176, s23, v195
	s_add_u32 vcc_lo, s2, 0x1c421680
	s_addc_u32 vcc_hi, s3, 0
	s_add_i32 m0, s24, 0x400
	v_lshl_add_u64 v[250:251], v[0:1], 0, vcc
	global_load_lds_dwordx4 v[250:251], off
	s_waitcnt lgkmcnt(0)
	v_mfma_f32_32x32x16_bf16 v[82:97], v[172:175], v[146:149], v[82:97]
	v_mfma_f32_32x32x16_bf16 v[114:129], v[204:207], v[146:149], v[114:129]
	ds_read_b128 v[172:175], v176 offset:57344
	ds_read_b128 v[204:207], v176 offset:49152
	v_add_u32_e32 v176, s23, v183
	s_waitcnt lgkmcnt(0)
	v_mfma_f32_32x32x16_bf16 v[82:97], v[172:175], v[142:145], v[82:97]
	v_mfma_f32_32x32x16_bf16 v[114:129], v[204:207], v[142:145], v[114:129]
	ds_read_b128 v[172:175], v176 offset:57344
	ds_read_b128 v[204:207], v176 offset:49152
	v_add_u32_e32 v176, s23, v193
	s_waitcnt lgkmcnt(0)
	v_mfma_f32_32x32x16_bf16 v[82:97], v[172:175], v[138:141], v[82:97]
	v_mfma_f32_32x32x16_bf16 v[114:129], v[204:207], v[138:141], v[114:129]
	ds_read_b128 v[172:175], v176 offset:57344
	ds_read_b128 v[204:207], v176 offset:49152
	v_add_u32_e32 v176, s23, v194
	s_waitcnt lgkmcnt(0)
	v_mfma_f32_32x32x16_bf16 v[82:97], v[172:175], v[134:137], v[82:97]
	v_mfma_f32_32x32x16_bf16 v[114:129], v[204:207], v[134:137], v[114:129]
	ds_read_b128 v[172:175], v176 offset:57344
	ds_read_b128 v[204:207], v176 offset:49152
	v_exp_f32_e32 v176, v102
	s_waitcnt lgkmcnt(0)
	v_mfma_f32_32x32x16_bf16 v[82:97], v[172:175], v[130:133], v[82:97]
	v_exp_f32_e32 v172, v98
	v_add_f32_e32 v98, 0, v208
	v_add_f32_e32 v98, v209, v98
	v_add_f32_e32 v98, v210, v98
	v_add_f32_e32 v98, v211, v98
	v_add_f32_e32 v98, v212, v98
	v_add_f32_e32 v98, v213, v98
	v_add_f32_e32 v98, v214, v98
	v_add_f32_e32 v98, v215, v98
	v_add_f32_e32 v98, v216, v98
	v_add_f32_e32 v98, v217, v98
	v_add_f32_e32 v98, v218, v98
	v_add_f32_e32 v98, v219, v98
	v_add_f32_e32 v98, v220, v98
	v_exp_f32_e32 v173, v99
	v_add_f32_e32 v98, v221, v98
	v_exp_f32_e32 v174, v100
	v_add_f32_e32 v98, v222, v98
	v_exp_f32_e32 v175, v101
	v_add_f32_e32 v98, v223, v98
	v_add_f32_e32 v98, v172, v98
	v_add_f32_e32 v98, v173, v98
	v_mfma_f32_32x32x16_bf16 v[114:129], v[204:207], v[130:133], v[114:129]
	v_exp_f32_e32 v204, v104
	v_add_f32_e32 v98, v174, v98
	v_exp_f32_e32 v205, v105
	v_add_f32_e32 v98, v175, v98
	v_exp_f32_e32 v206, v106
	v_add_f32_e32 v98, v176, v98
	v_exp_f32_e32 v207, v107
	v_add_f32_e32 v98, v177, v98
	v_add_f32_e32 v98, v204, v98
	v_add_f32_e32 v98, v205, v98
	v_add_f32_e32 v98, v206, v98
	v_add_f32_e32 v98, v207, v98
	v_add_f32_e32 v98, v224, v98
	v_add_f32_e32 v98, v225, v98
	v_add_f32_e32 v98, v226, v98
	v_add_f32_e32 v98, v227, v98
	v_add_f32_e32 v98, v112, v98
	v_cvt_pk_bf16_f32 v100, v208, v209
	v_cvt_pk_bf16_f32 v101, v210, v211
	v_cvt_pk_bf16_f32 v102, v212, v213
	v_cvt_pk_bf16_f32 v103, v214, v215
	v_cvt_pk_bf16_f32 v104, v216, v217
	v_cvt_pk_bf16_f32 v105, v218, v219
	v_cvt_pk_bf16_f32 v106, v220, v221
	v_cvt_pk_bf16_f32 v107, v222, v223
	v_cvt_pk_bf16_f32 v108, v172, v173
	v_cvt_pk_bf16_f32 v109, v174, v175
	v_cvt_pk_bf16_f32 v110, v176, v177
	v_cvt_pk_bf16_f32 v111, v204, v205
	v_cvt_pk_bf16_f32 v172, v206, v207
	v_cvt_pk_bf16_f32 v173, v224, v225
	v_cvt_pk_bf16_f32 v174, v226, v227
	v_cvt_pk_bf16_f32 v175, v112, v113
	v_add_u32_e32 v112, s19, v182
	ds_read_b64_tr_b16 v[204:205], v112 offset:0
	ds_read_b64_tr_b16 v[206:207], v112 offset:0x800
	ds_read_b64_tr_b16 v[208:209], v112 offset:0x1000
	ds_read_b64_tr_b16 v[210:211], v112 offset:0x1800
	ds_read_b64_tr_b16 v[212:213], v112 offset:0x2000
	ds_read_b64_tr_b16 v[214:215], v112 offset:0x2800
	ds_read_b64_tr_b16 v[216:217], v112 offset:0x3000
	ds_read_b64_tr_b16 v[218:219], v112 offset:0x3800
	v_add_f32_e32 v98, v113, v98
	v_mov_b32_e32 v99, v98
	s_nop 1
	v_permlane32_swap_b32_e32 v98, v99
	v_permlane32_swap_b32_e32 v100, v102
	v_permlane32_swap_b32_e32 v172, v174
	v_permlane32_swap_b32_e32 v101, v103
	v_permlane32_swap_b32_e32 v104, v106
	v_permlane32_swap_b32_e32 v105, v107
	v_permlane32_swap_b32_e32 v108, v110
	v_permlane32_swap_b32_e32 v109, v111
	v_permlane32_swap_b32_e32 v173, v175
	s_waitcnt lgkmcnt(6)
; #define SBAR() __builtin_amdgcn_sched_barrier(0)
; __device__ __forceinline__ float max3f(float a, float b, float c) { return __builtin_fmaxf(__builtin_fmaxf(a, b), c); }
; template <bool FIRST, bool MLA>
; __device__ __forceinline__ void partialSM(f32x16& p0, f32x16& p1, f32x16& negm, float& m_reg, float& alpha) {
;   float a = max3f(p0[0], p0[1], p1[0]), b = max3f(p0[2], p0[3], p1[1]); a = max3f(a, p1[2], p1[3]);
; #pragma unroll
;   for (int r = 4; r < 16; r += 4) { a = max3f(a, p0[r], p0[r + 1]); b = max3f(b, p0[r + 2], p0[r + 3]); a = max3f(a, p1[r], p1[r + 1]); b = max3f(b, p1[r + 2], p1[r + 3]); }
;   float pmax = fmaxf(a, b);
;   { auto rr = __builtin_amdgcn_permlane32_swap(__float_as_uint(pmax), __float_as_uint(pmax), false, false);
;     pmax = fmaxf(__uint_as_float(rr[0]), __uint_as_float(rr[1])); }
;   alpha = 1.f;
;   if constexpr (MLA) {
;     if (FIRST) m_reg = pmax;
;     else if (!__builtin_expect(__all(pmax - m_reg <= THR2), 1)) { const float mn = fmaxf(m_reg, pmax); alpha = __builtin_amdgcn_exp2f(m_reg - mn); m_reg = mn; }
; #pragma unroll
;     for (int r = 0; r < 16; ++r) { p0[r] -= m_reg; p1[r] -= m_reg; }
;   } else
;   if (FIRST || __builtin_expect(__any(pmax > THR2), 0)) {
; template <int D0> __device__ __forceinline__ void pv_one(f32x16& od, int vb, bf16x8 pa0, bf16x8 pa1, bf16x8 pa2, bf16x8 pa3) {
;   const s16x4 l0 = tr_read<v_rd_off(D0, 0, 0)>(vb), h0 = tr_read<v_rd_off(D0, 0, 1)>(vb), l1 = tr_read<v_rd_off(D0, 1, 0)>(vb), h1 = tr_read<v_rd_off(D0, 1, 1)>(vb);
;   const s16x4 l2 = tr_read<v_rd_off(D0, 2, 0)>(vb), h2 = tr_read<v_rd_off(D0, 2, 1)>(vb), l3 = tr_read<v_rd_off(D0, 3, 0)>(vb), h3 = tr_read<v_rd_off(D0, 3, 1)>(vb);
;   asm volatile("s_waitcnt lgkmcnt(0)" ::: "memory"); SBAR();
;     ...
;   od = __builtin_amdgcn_mfma_f32_32x32x16_bf16(pa0, PK(l0, h0), od, 0, 0, 0);
;   od = __builtin_amdgcn_mfma_f32_32x32x16_bf16(pa1, PK(l1, h1), od, 0, 0, 0);
;   od = __builtin_amdgcn_mfma_f32_32x32x16_bf16(pa2, PK(l2, h2), od, 0, 0, 0);
;   od = __builtin_amdgcn_mfma_f32_32x32x16_bf16(pa3, PK(l3, h3), od, 0, 0, 0);
;     ...
; }
; __device__ __forceinline__ void pv_d0(f32x16* o, int vb, bf16x8 pa0, bf16x8 pa1, bf16x8 pa2, bf16x8 pa3) {
;   pv_one<0>(o[0], vb, pa0, pa1, pa2, pa3); pv_one<1>(o[1], vb, pa0, pa1, pa2, pa3); pv_one<2>(o[2], vb, pa0, pa1, pa2, pa3); pv_one<3>(o[3], vb, pa0, pa1, pa2, pa3);
	v_mfma_f32_32x32x16_bf16 v[2:17], v[100:103], v[204:207], v[2:17]
	ds_read_b64_tr_b16 v[204:205], v112 offset:0x200
	ds_read_b64_tr_b16 v[206:207], v112 offset:0xa00
	s_waitcnt lgkmcnt(6)
	v_mfma_f32_32x32x16_bf16 v[2:17], v[104:107], v[208:211], v[2:17]
	ds_read_b64_tr_b16 v[208:209], v112 offset:0x1200
	ds_read_b64_tr_b16 v[210:211], v112 offset:0x1a00
	s_waitcnt lgkmcnt(6)
	v_mfma_f32_32x32x16_bf16 v[2:17], v[108:111], v[212:215], v[2:17]
	ds_read_b64_tr_b16 v[212:213], v112 offset:0x2200
	ds_read_b64_tr_b16 v[214:215], v112 offset:0x2a00
	s_waitcnt lgkmcnt(6)
	v_mfma_f32_32x32x16_bf16 v[2:17], v[172:175], v[216:219], v[2:17]
	ds_read_b64_tr_b16 v[216:217], v112 offset:0x3200
	ds_read_b64_tr_b16 v[218:219], v112 offset:0x3a00
	s_waitcnt lgkmcnt(6)
	v_mfma_f32_32x32x16_bf16 v[50:65], v[100:103], v[204:207], v[50:65]
	ds_read_b64_tr_b16 v[204:205], v112 offset:0x400
	ds_read_b64_tr_b16 v[206:207], v112 offset:0xc00
	s_waitcnt lgkmcnt(6)
	v_mfma_f32_32x32x16_bf16 v[50:65], v[104:107], v[208:211], v[50:65]
	ds_read_b64_tr_b16 v[208:209], v112 offset:0x1400
	ds_read_b64_tr_b16 v[210:211], v112 offset:0x1c00
	s_waitcnt lgkmcnt(6)
	v_mfma_f32_32x32x16_bf16 v[50:65], v[108:111], v[212:215], v[50:65]
	ds_read_b64_tr_b16 v[212:213], v112 offset:0x2400
	ds_read_b64_tr_b16 v[214:215], v112 offset:0x2c00
	s_waitcnt lgkmcnt(6)
	v_mfma_f32_32x32x16_bf16 v[50:65], v[172:175], v[216:219], v[50:65]
	ds_read_b64_tr_b16 v[216:217], v112 offset:0x3400
	ds_read_b64_tr_b16 v[218:219], v112 offset:0x3c00
	s_waitcnt lgkmcnt(6)
	v_mfma_f32_32x32x16_bf16 v[34:49], v[100:103], v[204:207], v[34:49]
	ds_read_b64_tr_b16 v[204:205], v112 offset:0x600
	ds_read_b64_tr_b16 v[206:207], v112 offset:0xe00
	s_waitcnt lgkmcnt(6)
	v_mfma_f32_32x32x16_bf16 v[34:49], v[104:107], v[208:211], v[34:49]
	ds_read_b64_tr_b16 v[208:209], v112 offset:0x1600
	ds_read_b64_tr_b16 v[210:211], v112 offset:0x1e00
	s_waitcnt lgkmcnt(6)
	v_mfma_f32_32x32x16_bf16 v[34:49], v[108:111], v[212:215], v[34:49]
	ds_read_b64_tr_b16 v[212:213], v112 offset:0x2600
	ds_read_b64_tr_b16 v[214:215], v112 offset:0x2e00
	s_waitcnt lgkmcnt(6)
	v_mfma_f32_32x32x16_bf16 v[34:49], v[172:175], v[216:219], v[34:49]
	ds_read_b64_tr_b16 v[216:217], v112 offset:0x3600
	ds_read_b64_tr_b16 v[218:219], v112 offset:0x3e00
	s_waitcnt lgkmcnt(6)
	v_mfma_f32_32x32x16_bf16 v[18:33], v[100:103], v[204:207], v[18:33]
	v_max_f32_e32 v100, v115, v115
	v_max_f32_e32 v101, v114, v114
	v_max_f32_e32 v100, v101, v100
	v_max3_f32 v101, v116, v117, v83
	v_max3_f32 v100, v100, v82, v84
	v_max3_f32 v100, v100, v85, v118
	v_max3_f32 v101, v101, v120, v121
	s_waitcnt lgkmcnt(4)
	v_mfma_f32_32x32x16_bf16 v[18:33], v[104:107], v[208:211], v[18:33]
	v_max3_f32 v100, v100, v119, v86
	v_max3_f32 v101, v101, v88, v89
	v_max3_f32 v100, v100, v87, v122
	v_max3_f32 v101, v101, v124, v125
	v_max3_f32 v100, v100, v123, v90
	v_max3_f32 v101, v101, v92, v93
	v_max3_f32 v100, v100, v91, v126
	s_waitcnt lgkmcnt(2)
	v_mfma_f32_32x32x16_bf16 v[18:33], v[108:111], v[212:215], v[18:33]
	v_max3_f32 v101, v101, v128, v129
	v_max3_f32 v100, v100, v127, v94
	v_max3_f32 v101, v101, v96, v97
	v_max3_f32 v100, v100, v95, v101
	v_mov_b32_e32 v101, v100
	s_nop 1
	v_permlane32_swap_b32_e32 v100, v101
	s_waitcnt lgkmcnt(0)
	v_mfma_f32_32x32x16_bf16 v[18:33], v[172:175], v[216:219], v[18:33]
	v_max_f32_e32 v101, v101, v101
	v_max_f32_e32 v100, v100, v100
	v_max_f32_e32 v100, v100, v101
	v_cmp_lt_f32_e32 vcc, s40, v100
	v_mov_b32_e32 v172, 1.0
	s_cbranch_vccnz .LBB0_138
	v_cmp_gt_f32_e32 vcc, 1.0, v172
	s_cbranch_vccz .LBB0_135
